# v_li + M1 epilogue lane-transpose network (permlane32/16 swap + cndmask_dpp): quad-contiguous 64B store requests
# speedup vs baseline: 1.0130x; 1.0037x over previous
.LBB0_958:
	v_and_b32_e32 v192, 28, v0
	v_and_b32_e32 v175, -16, v146
	v_add_u32_e32 v175, v175, v192
	v_lshlrev_b32_e32 v175, 13, v175
	v_lshrrev_b32_e32 v193, 3, v0
	v_and_b32_e32 v193, 4, v193
	v_and_b32_e32 v192, 3, v0
	v_or_b32_e32 v192, v192, v193
	v_lshrrev_b32_e32 v193, 5, v226
	v_lshlrev_b32_e32 v193, 6, v193
	v_lshl_or_b32 v192, v192, 4, v193
	v_lshl_or_b32 v192, s59, 9, v192
	v_or_b32_e32 v175, v175, v192
	v_pk_mul_f32 v[126:127], v[126:127], v[140:141] op_sel_hi:[1,0]
	v_pk_mul_f32 v[130:131], v[130:131], v[140:141] op_sel_hi:[1,0]
	v_pk_mul_f32 v[128:129], v[128:129], v[140:141] op_sel_hi:[1,0]
	v_max_f32_e32 v126, 0, v126
	v_pk_mul_f32 v[132:133], v[132:133], v[140:141] op_sel_hi:[1,0]
	v_mul_f32_e32 v141, v126, v126
	v_max_f32_e32 v126, 0, v131
	v_max_f32_e32 v127, 0, v127
	v_max_f32_e32 v128, 0, v128
	v_max_f32_e32 v130, 0, v130
	v_mul_f32_e32 v126, v126, v126
	v_mul_f32_e32 v131, v127, v127
	v_max_f32_e32 v127, 0, v132
	v_mul_f32_e32 v132, v128, v128
	v_max_f32_e32 v128, 0, v133
	v_max_f32_e32 v129, 0, v129
	v_pk_mul_f32 v[118:119], v[118:119], v[140:141] op_sel_hi:[1,0]
	v_mul_f32_e32 v130, v130, v130
	v_mul_f32_e32 v127, v127, v127
	v_mul_f32_e32 v128, v128, v128
	v_mul_f32_e32 v129, v129, v129
	v_cvt_pk_bf16_f32 v126, v130, v126
	v_pk_mul_f32 v[122:123], v[122:123], v[140:141] op_sel_hi:[1,0]
	v_pk_mul_f32 v[120:121], v[120:121], v[140:141] op_sel_hi:[1,0]
	v_max_f32_e32 v118, 0, v118
	v_cvt_pk_bf16_f32 v127, v127, v128
	v_cvt_pk_bf16_f32 v128, v141, v131
	v_cvt_pk_bf16_f32 v129, v132, v129
	v_pk_mul_f32 v[124:125], v[124:125], v[140:141] op_sel_hi:[1,0]
	v_max_f32_e32 v119, 0, v119
	v_mul_f32_e32 v194, v118, v118
	v_max_f32_e32 v118, 0, v123
	v_max_f32_e32 v120, 0, v120
	v_max_f32_e32 v122, 0, v122
	v_mul_f32_e32 v118, v118, v118
	v_mul_f32_e32 v123, v119, v119
	v_max_f32_e32 v119, 0, v124
	v_mul_f32_e32 v124, v120, v120
	v_max_f32_e32 v120, 0, v125
	v_max_f32_e32 v121, 0, v121
	v_mul_f32_e32 v122, v122, v122
	v_mul_f32_e32 v119, v119, v119
	v_mul_f32_e32 v120, v120, v120
	v_mul_f32_e32 v121, v121, v121
	v_cvt_pk_bf16_f32 v118, v122, v118
	v_cvt_pk_bf16_f32 v119, v119, v120
	v_cvt_pk_bf16_f32 v120, v194, v123
	v_cvt_pk_bf16_f32 v121, v124, v121
	v_pk_mul_f32 v[110:111], v[110:111], v[144:145] op_sel_hi:[1,0]
	v_pk_mul_f32 v[114:115], v[114:115], v[144:145] op_sel_hi:[1,0]
	v_pk_mul_f32 v[112:113], v[112:113], v[144:145] op_sel_hi:[1,0]
	v_max_f32_e32 v110, 0, v110
	v_pk_mul_f32 v[116:117], v[116:117], v[144:145] op_sel_hi:[1,0]
	v_mul_f32_e32 v194, v110, v110
	v_max_f32_e32 v110, 0, v115
	v_max_f32_e32 v111, 0, v111
	v_max_f32_e32 v112, 0, v112
	v_max_f32_e32 v114, 0, v114
	v_mul_f32_e32 v110, v110, v110
	v_mul_f32_e32 v115, v111, v111
	v_max_f32_e32 v111, 0, v116
	v_mul_f32_e32 v116, v112, v112
	v_max_f32_e32 v112, 0, v117
	v_max_f32_e32 v113, 0, v113
	v_pk_mul_f32 v[102:103], v[102:103], v[144:145] op_sel_hi:[1,0]
	v_mul_f32_e32 v114, v114, v114
	v_mul_f32_e32 v111, v111, v111
	v_mul_f32_e32 v112, v112, v112
	v_mul_f32_e32 v113, v113, v113
	v_cvt_pk_bf16_f32 v110, v114, v110
	v_pk_mul_f32 v[106:107], v[106:107], v[144:145] op_sel_hi:[1,0]
	v_pk_mul_f32 v[104:105], v[104:105], v[144:145] op_sel_hi:[1,0]
	v_max_f32_e32 v102, 0, v102
	v_cvt_pk_bf16_f32 v111, v111, v112
	v_cvt_pk_bf16_f32 v112, v194, v115
	v_cvt_pk_bf16_f32 v113, v116, v113
	v_pk_mul_f32 v[108:109], v[108:109], v[144:145] op_sel_hi:[1,0]
	v_max_f32_e32 v103, 0, v103
	v_mul_f32_e32 v194, v102, v102
	v_max_f32_e32 v102, 0, v107
	v_max_f32_e32 v104, 0, v104
	v_max_f32_e32 v106, 0, v106
	v_mul_f32_e32 v102, v102, v102
	v_mul_f32_e32 v107, v103, v103
	v_max_f32_e32 v103, 0, v108
	v_mul_f32_e32 v108, v104, v104
	v_max_f32_e32 v104, 0, v109
	v_max_f32_e32 v105, 0, v105
	v_mul_f32_e32 v106, v106, v106
	v_mul_f32_e32 v103, v103, v103
	v_mul_f32_e32 v104, v104, v104
	v_mul_f32_e32 v105, v105, v105
	v_cvt_pk_bf16_f32 v102, v106, v102
	v_cvt_pk_bf16_f32 v103, v103, v104
	v_cvt_pk_bf16_f32 v104, v194, v107
	v_cvt_pk_bf16_f32 v105, v108, v105
	s_nop 1
	v_permlane32_swap_b32_e32 v126, v118
	v_permlane32_swap_b32_e32 v127, v119
	v_permlane32_swap_b32_e32 v128, v120
	v_permlane32_swap_b32_e32 v129, v121
	v_permlane32_swap_b32_e32 v110, v102
	v_permlane32_swap_b32_e32 v111, v103
	v_permlane32_swap_b32_e32 v112, v104
	v_permlane32_swap_b32_e32 v113, v105
	v_permlane16_swap_b32_e32 v126, v110
	v_permlane16_swap_b32_e32 v127, v111
	v_permlane16_swap_b32_e32 v128, v112
	v_permlane16_swap_b32_e32 v129, v113
	v_permlane16_swap_b32_e32 v118, v102
	v_permlane16_swap_b32_e32 v119, v103
	v_permlane16_swap_b32_e32 v120, v104
	v_permlane16_swap_b32_e32 v121, v105
	s_mov_b32 vcc_lo, 0x55555555
	s_mov_b32 vcc_hi, 0x55555555
	v_cndmask_b32_dpp v176, v110, v126, vcc quad_perm:[1,0,3,2] row_mask:0xf bank_mask:0xf
	v_cndmask_b32_dpp v177, v111, v127, vcc quad_perm:[1,0,3,2] row_mask:0xf bank_mask:0xf
	v_cndmask_b32_dpp v178, v112, v128, vcc quad_perm:[1,0,3,2] row_mask:0xf bank_mask:0xf
	v_cndmask_b32_dpp v179, v113, v129, vcc quad_perm:[1,0,3,2] row_mask:0xf bank_mask:0xf
	v_cndmask_b32_dpp v180, v102, v118, vcc quad_perm:[1,0,3,2] row_mask:0xf bank_mask:0xf
	v_cndmask_b32_dpp v181, v103, v119, vcc quad_perm:[1,0,3,2] row_mask:0xf bank_mask:0xf
	v_cndmask_b32_dpp v182, v104, v120, vcc quad_perm:[1,0,3,2] row_mask:0xf bank_mask:0xf
	v_cndmask_b32_dpp v183, v105, v121, vcc quad_perm:[1,0,3,2] row_mask:0xf bank_mask:0xf
	s_mov_b32 vcc_lo, 0xaaaaaaaa
	s_mov_b32 vcc_hi, 0xaaaaaaaa
	v_cndmask_b32_dpp v184, v126, v110, vcc quad_perm:[1,0,3,2] row_mask:0xf bank_mask:0xf
	v_cndmask_b32_dpp v185, v127, v111, vcc quad_perm:[1,0,3,2] row_mask:0xf bank_mask:0xf
	v_cndmask_b32_dpp v186, v128, v112, vcc quad_perm:[1,0,3,2] row_mask:0xf bank_mask:0xf
	v_cndmask_b32_dpp v187, v129, v113, vcc quad_perm:[1,0,3,2] row_mask:0xf bank_mask:0xf
	v_cndmask_b32_dpp v188, v118, v102, vcc quad_perm:[1,0,3,2] row_mask:0xf bank_mask:0xf
	v_cndmask_b32_dpp v189, v119, v103, vcc quad_perm:[1,0,3,2] row_mask:0xf bank_mask:0xf
	v_cndmask_b32_dpp v190, v120, v104, vcc quad_perm:[1,0,3,2] row_mask:0xf bank_mask:0xf
	v_cndmask_b32_dpp v191, v121, v105, vcc quad_perm:[1,0,3,2] row_mask:0xf bank_mask:0xf
	s_mov_b32 vcc_lo, 0x33333333
	s_mov_b32 vcc_hi, 0x33333333
	v_cndmask_b32_dpp v126, v180, v176, vcc quad_perm:[2,3,0,1] row_mask:0xf bank_mask:0xf
	v_cndmask_b32_dpp v127, v181, v177, vcc quad_perm:[2,3,0,1] row_mask:0xf bank_mask:0xf
	v_cndmask_b32_dpp v128, v182, v178, vcc quad_perm:[2,3,0,1] row_mask:0xf bank_mask:0xf
	v_cndmask_b32_dpp v129, v183, v179, vcc quad_perm:[2,3,0,1] row_mask:0xf bank_mask:0xf
	v_cndmask_b32_dpp v110, v188, v184, vcc quad_perm:[2,3,0,1] row_mask:0xf bank_mask:0xf
	v_cndmask_b32_dpp v111, v189, v185, vcc quad_perm:[2,3,0,1] row_mask:0xf bank_mask:0xf
	v_cndmask_b32_dpp v112, v190, v186, vcc quad_perm:[2,3,0,1] row_mask:0xf bank_mask:0xf
	v_cndmask_b32_dpp v113, v191, v187, vcc quad_perm:[2,3,0,1] row_mask:0xf bank_mask:0xf
	s_mov_b32 vcc_lo, 0xcccccccc
	s_mov_b32 vcc_hi, 0xcccccccc
	v_cndmask_b32_dpp v118, v176, v180, vcc quad_perm:[2,3,0,1] row_mask:0xf bank_mask:0xf
	v_cndmask_b32_dpp v119, v177, v181, vcc quad_perm:[2,3,0,1] row_mask:0xf bank_mask:0xf
	v_cndmask_b32_dpp v120, v178, v182, vcc quad_perm:[2,3,0,1] row_mask:0xf bank_mask:0xf
	v_cndmask_b32_dpp v121, v179, v183, vcc quad_perm:[2,3,0,1] row_mask:0xf bank_mask:0xf
	v_cndmask_b32_dpp v102, v184, v188, vcc quad_perm:[2,3,0,1] row_mask:0xf bank_mask:0xf
	v_cndmask_b32_dpp v103, v185, v189, vcc quad_perm:[2,3,0,1] row_mask:0xf bank_mask:0xf
	v_cndmask_b32_dpp v104, v186, v190, vcc quad_perm:[2,3,0,1] row_mask:0xf bank_mask:0xf
	v_cndmask_b32_dpp v105, v187, v191, vcc quad_perm:[2,3,0,1] row_mask:0xf bank_mask:0xf
	global_store_dwordx4 v175, v[126:129], s[4:5] sc1
	v_add_u32_e32 v193, 0x2000, v175
	global_store_dwordx4 v193, v[110:113], s[4:5] sc1
	v_add_u32_e32 v195, 0x4000, v175
	global_store_dwordx4 v195, v[118:121], s[4:5] sc1
	v_add_u32_e32 v196, 0x6000, v175
	global_store_dwordx4 v196, v[102:105], s[4:5] sc1
	v_pk_mul_f32 v[94:95], v[94:95], v[148:149] op_sel_hi:[1,0]
	v_pk_mul_f32 v[98:99], v[98:99], v[148:149] op_sel_hi:[1,0]
	v_pk_mul_f32 v[96:97], v[96:97], v[148:149] op_sel_hi:[1,0]
	v_max_f32_e32 v94, 0, v94
	v_pk_mul_f32 v[100:101], v[100:101], v[148:149] op_sel_hi:[1,0]
	v_mul_f32_e32 v104, v94, v94
	v_max_f32_e32 v94, 0, v99
	v_max_f32_e32 v95, 0, v95
	v_max_f32_e32 v96, 0, v96
	v_max_f32_e32 v98, 0, v98
	v_mul_f32_e32 v94, v94, v94
	v_mul_f32_e32 v99, v95, v95
	v_max_f32_e32 v95, 0, v100
	v_mul_f32_e32 v100, v96, v96
	v_max_f32_e32 v96, 0, v101
	v_max_f32_e32 v97, 0, v97
	v_pk_mul_f32 v[86:87], v[86:87], v[148:149] op_sel_hi:[1,0]
	v_mul_f32_e32 v98, v98, v98
	v_mul_f32_e32 v95, v95, v95
	v_mul_f32_e32 v96, v96, v96
	v_mul_f32_e32 v97, v97, v97
	v_cvt_pk_bf16_f32 v94, v98, v94
	v_pk_mul_f32 v[90:91], v[90:91], v[148:149] op_sel_hi:[1,0]
	v_pk_mul_f32 v[88:89], v[88:89], v[148:149] op_sel_hi:[1,0]
	v_max_f32_e32 v86, 0, v86
	v_cvt_pk_bf16_f32 v95, v95, v96
	v_cvt_pk_bf16_f32 v96, v104, v99
	v_cvt_pk_bf16_f32 v97, v100, v97
	v_pk_mul_f32 v[92:93], v[92:93], v[148:149] op_sel_hi:[1,0]
	v_max_f32_e32 v87, 0, v87
	v_mul_f32_e32 v194, v86, v86
	v_max_f32_e32 v86, 0, v91
	v_max_f32_e32 v88, 0, v88
	v_max_f32_e32 v90, 0, v90
	v_mul_f32_e32 v86, v86, v86
	v_mul_f32_e32 v91, v87, v87
	v_max_f32_e32 v87, 0, v92
	v_mul_f32_e32 v92, v88, v88
	v_max_f32_e32 v88, 0, v93
	v_max_f32_e32 v89, 0, v89
	v_mul_f32_e32 v90, v90, v90
	v_mul_f32_e32 v87, v87, v87
	v_mul_f32_e32 v88, v88, v88
	v_mul_f32_e32 v89, v89, v89
	v_cvt_pk_bf16_f32 v86, v90, v86
	v_cvt_pk_bf16_f32 v87, v87, v88
	v_cvt_pk_bf16_f32 v88, v194, v91
	v_cvt_pk_bf16_f32 v89, v92, v89
	v_pk_mul_f32 v[78:79], v[78:79], v[150:151] op_sel_hi:[1,0]
	v_pk_mul_f32 v[82:83], v[82:83], v[150:151] op_sel_hi:[1,0]
	v_pk_mul_f32 v[80:81], v[80:81], v[150:151] op_sel_hi:[1,0]
	v_max_f32_e32 v78, 0, v78
	v_pk_mul_f32 v[84:85], v[84:85], v[150:151] op_sel_hi:[1,0]
	v_mul_f32_e32 v194, v78, v78
	v_max_f32_e32 v78, 0, v83
	v_max_f32_e32 v79, 0, v79
	v_max_f32_e32 v80, 0, v80
	v_max_f32_e32 v82, 0, v82
	v_mul_f32_e32 v78, v78, v78
	v_mul_f32_e32 v83, v79, v79
	v_max_f32_e32 v79, 0, v84
	v_mul_f32_e32 v84, v80, v80
	v_max_f32_e32 v80, 0, v85
	v_max_f32_e32 v81, 0, v81
	v_pk_mul_f32 v[72:73], v[72:73], v[150:151] op_sel_hi:[1,0]
	v_pk_mul_f32 v[70:71], v[70:71], v[150:151] op_sel_hi:[1,0]
	v_mul_f32_e32 v82, v82, v82
	v_mul_f32_e32 v79, v79, v79
	v_mul_f32_e32 v80, v80, v80
	v_mul_f32_e32 v81, v81, v81
	v_cvt_pk_bf16_f32 v78, v82, v78
	v_pk_mul_f32 v[76:77], v[76:77], v[150:151] op_sel_hi:[1,0]
	v_pk_mul_f32 v[74:75], v[74:75], v[150:151] op_sel_hi:[1,0]
	v_max_f32_e32 v70, 0, v70
	v_max_f32_e32 v71, 0, v71
	v_max_f32_e32 v72, 0, v72
	v_cvt_pk_bf16_f32 v79, v79, v80
	v_cvt_pk_bf16_f32 v80, v194, v83
	v_cvt_pk_bf16_f32 v81, v84, v81
	v_max_f32_e32 v74, 0, v74
	v_max_f32_e32 v73, 0, v73
	v_mul_f32_e32 v194, v70, v70
	v_max_f32_e32 v70, 0, v75
	v_mul_f32_e32 v75, v71, v71
	v_max_f32_e32 v71, 0, v76
	v_mul_f32_e32 v76, v72, v72
	v_max_f32_e32 v72, 0, v77
	v_mul_f32_e32 v70, v70, v70
	v_mul_f32_e32 v71, v71, v71
	v_mul_f32_e32 v72, v72, v72
	v_pk_mul_f32 v[62:63], v[62:63], v[136:137] op_sel_hi:[1,0]
	v_mul_f32_e32 v74, v74, v74
	v_mul_f32_e32 v73, v73, v73
	v_cvt_pk_bf16_f32 v70, v74, v70
	v_cvt_pk_bf16_f32 v71, v71, v72
	v_cvt_pk_bf16_f32 v72, v194, v75
	v_pk_mul_f32 v[66:67], v[66:67], v[136:137] op_sel_hi:[1,0]
	v_pk_mul_f32 v[64:65], v[64:65], v[136:137] op_sel_hi:[1,0]
	v_max_f32_e32 v62, 0, v62
	v_cvt_pk_bf16_f32 v73, v76, v73
	s_nop 1
	v_permlane32_swap_b32_e32 v94, v86
	v_permlane32_swap_b32_e32 v95, v87
	v_permlane32_swap_b32_e32 v96, v88
	v_permlane32_swap_b32_e32 v97, v89
	v_permlane32_swap_b32_e32 v78, v70
	v_permlane32_swap_b32_e32 v79, v71
	v_permlane32_swap_b32_e32 v80, v72
	v_permlane32_swap_b32_e32 v81, v73
	v_permlane16_swap_b32_e32 v94, v78
	v_permlane16_swap_b32_e32 v95, v79
	v_permlane16_swap_b32_e32 v96, v80
	v_permlane16_swap_b32_e32 v97, v81
	v_permlane16_swap_b32_e32 v86, v70
	v_permlane16_swap_b32_e32 v87, v71
	v_permlane16_swap_b32_e32 v88, v72
	v_permlane16_swap_b32_e32 v89, v73
	s_mov_b32 vcc_lo, 0x55555555
	s_mov_b32 vcc_hi, 0x55555555
	v_cndmask_b32_dpp v176, v78, v94, vcc quad_perm:[1,0,3,2] row_mask:0xf bank_mask:0xf
	v_cndmask_b32_dpp v177, v79, v95, vcc quad_perm:[1,0,3,2] row_mask:0xf bank_mask:0xf
	v_cndmask_b32_dpp v178, v80, v96, vcc quad_perm:[1,0,3,2] row_mask:0xf bank_mask:0xf
	v_cndmask_b32_dpp v179, v81, v97, vcc quad_perm:[1,0,3,2] row_mask:0xf bank_mask:0xf
	v_cndmask_b32_dpp v180, v70, v86, vcc quad_perm:[1,0,3,2] row_mask:0xf bank_mask:0xf
	v_cndmask_b32_dpp v181, v71, v87, vcc quad_perm:[1,0,3,2] row_mask:0xf bank_mask:0xf
	v_cndmask_b32_dpp v182, v72, v88, vcc quad_perm:[1,0,3,2] row_mask:0xf bank_mask:0xf
	v_cndmask_b32_dpp v183, v73, v89, vcc quad_perm:[1,0,3,2] row_mask:0xf bank_mask:0xf
	s_mov_b32 vcc_lo, 0xaaaaaaaa
	s_mov_b32 vcc_hi, 0xaaaaaaaa
	v_cndmask_b32_dpp v184, v94, v78, vcc quad_perm:[1,0,3,2] row_mask:0xf bank_mask:0xf
	v_cndmask_b32_dpp v185, v95, v79, vcc quad_perm:[1,0,3,2] row_mask:0xf bank_mask:0xf
	v_cndmask_b32_dpp v186, v96, v80, vcc quad_perm:[1,0,3,2] row_mask:0xf bank_mask:0xf
	v_cndmask_b32_dpp v187, v97, v81, vcc quad_perm:[1,0,3,2] row_mask:0xf bank_mask:0xf
	v_cndmask_b32_dpp v188, v86, v70, vcc quad_perm:[1,0,3,2] row_mask:0xf bank_mask:0xf
	v_cndmask_b32_dpp v189, v87, v71, vcc quad_perm:[1,0,3,2] row_mask:0xf bank_mask:0xf
	v_cndmask_b32_dpp v190, v88, v72, vcc quad_perm:[1,0,3,2] row_mask:0xf bank_mask:0xf
	v_cndmask_b32_dpp v191, v89, v73, vcc quad_perm:[1,0,3,2] row_mask:0xf bank_mask:0xf
	s_mov_b32 vcc_lo, 0x33333333
	s_mov_b32 vcc_hi, 0x33333333
	v_cndmask_b32_dpp v94, v180, v176, vcc quad_perm:[2,3,0,1] row_mask:0xf bank_mask:0xf
	v_cndmask_b32_dpp v95, v181, v177, vcc quad_perm:[2,3,0,1] row_mask:0xf bank_mask:0xf
	v_cndmask_b32_dpp v96, v182, v178, vcc quad_perm:[2,3,0,1] row_mask:0xf bank_mask:0xf
	v_cndmask_b32_dpp v97, v183, v179, vcc quad_perm:[2,3,0,1] row_mask:0xf bank_mask:0xf
	v_cndmask_b32_dpp v78, v188, v184, vcc quad_perm:[2,3,0,1] row_mask:0xf bank_mask:0xf
	v_cndmask_b32_dpp v79, v189, v185, vcc quad_perm:[2,3,0,1] row_mask:0xf bank_mask:0xf
	v_cndmask_b32_dpp v80, v190, v186, vcc quad_perm:[2,3,0,1] row_mask:0xf bank_mask:0xf
	v_cndmask_b32_dpp v81, v191, v187, vcc quad_perm:[2,3,0,1] row_mask:0xf bank_mask:0xf
	s_mov_b32 vcc_lo, 0xcccccccc
	s_mov_b32 vcc_hi, 0xcccccccc
	v_cndmask_b32_dpp v86, v176, v180, vcc quad_perm:[2,3,0,1] row_mask:0xf bank_mask:0xf
	v_cndmask_b32_dpp v87, v177, v181, vcc quad_perm:[2,3,0,1] row_mask:0xf bank_mask:0xf
	v_cndmask_b32_dpp v88, v178, v182, vcc quad_perm:[2,3,0,1] row_mask:0xf bank_mask:0xf
	v_cndmask_b32_dpp v89, v179, v183, vcc quad_perm:[2,3,0,1] row_mask:0xf bank_mask:0xf
	v_cndmask_b32_dpp v70, v184, v188, vcc quad_perm:[2,3,0,1] row_mask:0xf bank_mask:0xf
	v_cndmask_b32_dpp v71, v185, v189, vcc quad_perm:[2,3,0,1] row_mask:0xf bank_mask:0xf
	v_cndmask_b32_dpp v72, v186, v190, vcc quad_perm:[2,3,0,1] row_mask:0xf bank_mask:0xf
	v_cndmask_b32_dpp v73, v187, v191, vcc quad_perm:[2,3,0,1] row_mask:0xf bank_mask:0xf
	v_add_u32_e32 v192, 0x40000, v175
	global_store_dwordx4 v192, v[94:97], s[4:5] sc1
	v_add_u32_e32 v193, 0x42000, v175
	global_store_dwordx4 v193, v[78:81], s[4:5] sc1
	v_add_u32_e32 v195, 0x44000, v175
	global_store_dwordx4 v195, v[86:89], s[4:5] sc1
	v_add_u32_e32 v196, 0x46000, v175
	global_store_dwordx4 v196, v[70:73], s[4:5] sc1
	v_pk_mul_f32 v[68:69], v[68:69], v[136:137] op_sel_hi:[1,0]
	v_max_f32_e32 v63, 0, v63
	v_mul_f32_e32 v72, v62, v62
	v_max_f32_e32 v62, 0, v67
	v_max_f32_e32 v64, 0, v64
	v_max_f32_e32 v66, 0, v66
	v_mul_f32_e32 v62, v62, v62
	v_mul_f32_e32 v67, v63, v63
	v_max_f32_e32 v63, 0, v68
	v_mul_f32_e32 v68, v64, v64
	v_max_f32_e32 v64, 0, v69
	v_max_f32_e32 v65, 0, v65
	v_pk_mul_f32 v[54:55], v[54:55], v[136:137] op_sel_hi:[1,0]
	v_mul_f32_e32 v66, v66, v66
	v_mul_f32_e32 v63, v63, v63
	v_mul_f32_e32 v64, v64, v64
	v_mul_f32_e32 v65, v65, v65
	v_cvt_pk_bf16_f32 v62, v66, v62
	v_pk_mul_f32 v[60:61], v[60:61], v[136:137] op_sel_hi:[1,0]
	v_pk_mul_f32 v[58:59], v[58:59], v[136:137] op_sel_hi:[1,0]
	v_pk_mul_f32 v[56:57], v[56:57], v[136:137] op_sel_hi:[1,0]
	v_max_f32_e32 v54, 0, v54
	v_max_f32_e32 v55, 0, v55
	v_cvt_pk_bf16_f32 v63, v63, v64
	v_cvt_pk_bf16_f32 v64, v72, v67
	v_cvt_pk_bf16_f32 v65, v68, v65
	v_max_f32_e32 v56, 0, v56
	v_max_f32_e32 v58, 0, v58
	v_mul_f32_e32 v194, v54, v54
	v_max_f32_e32 v54, 0, v59
	v_mul_f32_e32 v59, v55, v55
	v_max_f32_e32 v55, 0, v60
	v_mul_f32_e32 v54, v54, v54
	v_mul_f32_e32 v55, v55, v55
	v_mul_f32_e32 v60, v56, v56
	v_max_f32_e32 v56, 0, v61
	v_max_f32_e32 v57, 0, v57
	v_mul_f32_e32 v58, v58, v58
	v_mul_f32_e32 v56, v56, v56
	v_mul_f32_e32 v57, v57, v57
	v_cvt_pk_bf16_f32 v54, v58, v54
	v_cvt_pk_bf16_f32 v55, v55, v56
	v_pk_mul_f32 v[46:47], v[46:47], v[136:137] op_sel:[0,1]
	v_cvt_pk_bf16_f32 v56, v194, v59
	v_cvt_pk_bf16_f32 v57, v60, v57
	v_pk_mul_f32 v[50:51], v[50:51], v[136:137] op_sel:[0,1]
	v_pk_mul_f32 v[48:49], v[48:49], v[136:137] op_sel:[0,1]
	v_max_f32_e32 v46, 0, v46
	v_pk_mul_f32 v[52:53], v[52:53], v[136:137] op_sel:[0,1]
	v_max_f32_e32 v50, 0, v50
	v_mul_f32_e32 v194, v46, v46
	v_max_f32_e32 v46, 0, v51
	v_max_f32_e32 v47, 0, v47
	v_max_f32_e32 v48, 0, v48
	v_mul_f32_e32 v50, v50, v50
	v_mul_f32_e32 v46, v46, v46
	v_mul_f32_e32 v51, v47, v47
	v_max_f32_e32 v47, 0, v52
	v_mul_f32_e32 v52, v48, v48
	v_max_f32_e32 v48, 0, v53
	s_mov_b32 s13, 0x20000
	v_mul_f32_e32 v47, v47, v47
	v_max_f32_e32 v49, 0, v49
	v_mul_f32_e32 v48, v48, v48
	v_cvt_pk_bf16_f32 v46, v50, v46
	v_pk_mul_f32 v[40:41], v[40:41], v[136:137] op_sel:[0,1]
	v_pk_mul_f32 v[38:39], v[38:39], v[136:137] op_sel:[0,1]
	v_mul_f32_e32 v49, v49, v49
	v_cvt_pk_bf16_f32 v47, v47, v48
	v_cvt_pk_bf16_f32 v48, v194, v51
	v_pk_mul_f32 v[44:45], v[44:45], v[136:137] op_sel:[0,1]
	v_pk_mul_f32 v[42:43], v[42:43], v[136:137] op_sel:[0,1]
	v_max_f32_e32 v38, 0, v38
	v_max_f32_e32 v39, 0, v39
	v_max_f32_e32 v40, 0, v40
	v_cvt_pk_bf16_f32 v49, v52, v49
	s_mov_b64 s[22:23], 0x20000
	v_max_f32_e32 v41, 0, v41
	v_mul_f32_e32 v194, v38, v38
	v_max_f32_e32 v38, 0, v43
	v_mul_f32_e32 v43, v39, v39
	v_max_f32_e32 v39, 0, v44
	v_mul_f32_e32 v44, v40, v40
	v_max_f32_e32 v40, 0, v45
	v_mul_f32_e32 v39, v39, v39
	v_mul_f32_e32 v40, v40, v40
	v_pk_mul_f32 v[30:31], v[30:31], v[152:153] op_sel_hi:[1,0]
	v_max_f32_e32 v42, 0, v42
	v_mul_f32_e32 v38, v38, v38
	v_mul_f32_e32 v41, v41, v41
	v_cvt_pk_bf16_f32 v39, v39, v40
	v_cvt_pk_bf16_f32 v40, v194, v43
	v_pk_mul_f32 v[34:35], v[34:35], v[152:153] op_sel_hi:[1,0]
	v_pk_mul_f32 v[32:33], v[32:33], v[152:153] op_sel_hi:[1,0]
	v_max_f32_e32 v30, 0, v30
	v_mul_f32_e32 v42, v42, v42
	v_cvt_pk_bf16_f32 v38, v42, v38
	v_cvt_pk_bf16_f32 v41, v44, v41
	s_nop 1
	v_permlane32_swap_b32_e32 v62, v54
	v_permlane32_swap_b32_e32 v63, v55
	v_permlane32_swap_b32_e32 v64, v56
	v_permlane32_swap_b32_e32 v65, v57
	v_permlane32_swap_b32_e32 v46, v38
	v_permlane32_swap_b32_e32 v47, v39
	v_permlane32_swap_b32_e32 v48, v40
	v_permlane32_swap_b32_e32 v49, v41
	v_permlane16_swap_b32_e32 v62, v46
	v_permlane16_swap_b32_e32 v63, v47
	v_permlane16_swap_b32_e32 v64, v48
	v_permlane16_swap_b32_e32 v65, v49
	v_permlane16_swap_b32_e32 v54, v38
	v_permlane16_swap_b32_e32 v55, v39
	v_permlane16_swap_b32_e32 v56, v40
	v_permlane16_swap_b32_e32 v57, v41
	s_mov_b32 vcc_lo, 0x55555555
	s_mov_b32 vcc_hi, 0x55555555
	v_cndmask_b32_dpp v176, v46, v62, vcc quad_perm:[1,0,3,2] row_mask:0xf bank_mask:0xf
	v_cndmask_b32_dpp v177, v47, v63, vcc quad_perm:[1,0,3,2] row_mask:0xf bank_mask:0xf
	v_cndmask_b32_dpp v178, v48, v64, vcc quad_perm:[1,0,3,2] row_mask:0xf bank_mask:0xf
	v_cndmask_b32_dpp v179, v49, v65, vcc quad_perm:[1,0,3,2] row_mask:0xf bank_mask:0xf
	v_cndmask_b32_dpp v180, v38, v54, vcc quad_perm:[1,0,3,2] row_mask:0xf bank_mask:0xf
	v_cndmask_b32_dpp v181, v39, v55, vcc quad_perm:[1,0,3,2] row_mask:0xf bank_mask:0xf
	v_cndmask_b32_dpp v182, v40, v56, vcc quad_perm:[1,0,3,2] row_mask:0xf bank_mask:0xf
	v_cndmask_b32_dpp v183, v41, v57, vcc quad_perm:[1,0,3,2] row_mask:0xf bank_mask:0xf
	s_mov_b32 vcc_lo, 0xaaaaaaaa
	s_mov_b32 vcc_hi, 0xaaaaaaaa
	v_cndmask_b32_dpp v184, v62, v46, vcc quad_perm:[1,0,3,2] row_mask:0xf bank_mask:0xf
	v_cndmask_b32_dpp v185, v63, v47, vcc quad_perm:[1,0,3,2] row_mask:0xf bank_mask:0xf
	v_cndmask_b32_dpp v186, v64, v48, vcc quad_perm:[1,0,3,2] row_mask:0xf bank_mask:0xf
	v_cndmask_b32_dpp v187, v65, v49, vcc quad_perm:[1,0,3,2] row_mask:0xf bank_mask:0xf
	v_cndmask_b32_dpp v188, v54, v38, vcc quad_perm:[1,0,3,2] row_mask:0xf bank_mask:0xf
	v_cndmask_b32_dpp v189, v55, v39, vcc quad_perm:[1,0,3,2] row_mask:0xf bank_mask:0xf
	v_cndmask_b32_dpp v190, v56, v40, vcc quad_perm:[1,0,3,2] row_mask:0xf bank_mask:0xf
	v_cndmask_b32_dpp v191, v57, v41, vcc quad_perm:[1,0,3,2] row_mask:0xf bank_mask:0xf
	s_mov_b32 vcc_lo, 0x33333333
	s_mov_b32 vcc_hi, 0x33333333
	v_cndmask_b32_dpp v62, v180, v176, vcc quad_perm:[2,3,0,1] row_mask:0xf bank_mask:0xf
	v_cndmask_b32_dpp v63, v181, v177, vcc quad_perm:[2,3,0,1] row_mask:0xf bank_mask:0xf
	v_cndmask_b32_dpp v64, v182, v178, vcc quad_perm:[2,3,0,1] row_mask:0xf bank_mask:0xf
	v_cndmask_b32_dpp v65, v183, v179, vcc quad_perm:[2,3,0,1] row_mask:0xf bank_mask:0xf
	v_cndmask_b32_dpp v46, v188, v184, vcc quad_perm:[2,3,0,1] row_mask:0xf bank_mask:0xf
	v_cndmask_b32_dpp v47, v189, v185, vcc quad_perm:[2,3,0,1] row_mask:0xf bank_mask:0xf
	v_cndmask_b32_dpp v48, v190, v186, vcc quad_perm:[2,3,0,1] row_mask:0xf bank_mask:0xf
	v_cndmask_b32_dpp v49, v191, v187, vcc quad_perm:[2,3,0,1] row_mask:0xf bank_mask:0xf
	s_mov_b32 vcc_lo, 0xcccccccc
	s_mov_b32 vcc_hi, 0xcccccccc
	v_cndmask_b32_dpp v54, v176, v180, vcc quad_perm:[2,3,0,1] row_mask:0xf bank_mask:0xf
	v_cndmask_b32_dpp v55, v177, v181, vcc quad_perm:[2,3,0,1] row_mask:0xf bank_mask:0xf
	v_cndmask_b32_dpp v56, v178, v182, vcc quad_perm:[2,3,0,1] row_mask:0xf bank_mask:0xf
	v_cndmask_b32_dpp v57, v179, v183, vcc quad_perm:[2,3,0,1] row_mask:0xf bank_mask:0xf
	v_cndmask_b32_dpp v38, v184, v188, vcc quad_perm:[2,3,0,1] row_mask:0xf bank_mask:0xf
	v_cndmask_b32_dpp v39, v185, v189, vcc quad_perm:[2,3,0,1] row_mask:0xf bank_mask:0xf
	v_cndmask_b32_dpp v40, v186, v190, vcc quad_perm:[2,3,0,1] row_mask:0xf bank_mask:0xf
	v_cndmask_b32_dpp v41, v187, v191, vcc quad_perm:[2,3,0,1] row_mask:0xf bank_mask:0xf
	v_add_u32_e32 v192, 0x100000, v175
	global_store_dwordx4 v192, v[62:65], s[4:5] sc1
	v_add_u32_e32 v193, 0x102000, v175
	global_store_dwordx4 v193, v[46:49], s[4:5] sc1
	v_add_u32_e32 v195, 0x104000, v175
	global_store_dwordx4 v195, v[54:57], s[4:5] sc1
	v_add_u32_e32 v196, 0x106000, v175
	global_store_dwordx4 v196, v[38:41], s[4:5] sc1
	v_pk_mul_f32 v[36:37], v[36:37], v[152:153] op_sel_hi:[1,0]
	v_max_f32_e32 v34, 0, v34
	v_mul_f32_e32 v40, v30, v30
	v_max_f32_e32 v30, 0, v35
	v_max_f32_e32 v31, 0, v31
	v_max_f32_e32 v32, 0, v32
	v_mul_f32_e32 v34, v34, v34
	v_mul_f32_e32 v30, v30, v30
	v_mul_f32_e32 v35, v31, v31
	v_max_f32_e32 v31, 0, v36
	v_mul_f32_e32 v36, v32, v32
	v_max_f32_e32 v32, 0, v37
	v_mul_f32_e32 v31, v31, v31
	v_max_f32_e32 v33, 0, v33
	v_mul_f32_e32 v32, v32, v32
	v_cvt_pk_bf16_f32 v30, v34, v30
	v_pk_mul_f32 v[24:25], v[24:25], v[152:153] op_sel_hi:[1,0]
	v_pk_mul_f32 v[22:23], v[22:23], v[152:153] op_sel_hi:[1,0]
	v_mul_f32_e32 v33, v33, v33
	v_cvt_pk_bf16_f32 v31, v31, v32
	v_cvt_pk_bf16_f32 v32, v40, v35
	v_pk_mul_f32 v[28:29], v[28:29], v[152:153] op_sel_hi:[1,0]
	v_pk_mul_f32 v[26:27], v[26:27], v[152:153] op_sel_hi:[1,0]
	v_max_f32_e32 v22, 0, v22
	v_max_f32_e32 v23, 0, v23
	v_max_f32_e32 v24, 0, v24
	v_cvt_pk_bf16_f32 v33, v36, v33
	s_mov_b64 s[22:23], 0x40000
	v_max_f32_e32 v26, 0, v26
	v_mul_f32_e32 v194, v22, v22
	v_max_f32_e32 v22, 0, v27
	v_mul_f32_e32 v27, v23, v23
	v_max_f32_e32 v23, 0, v28
	v_mul_f32_e32 v28, v24, v24
	v_max_f32_e32 v24, 0, v29
	v_mul_f32_e32 v22, v22, v22
	v_mul_f32_e32 v23, v23, v23
	v_max_f32_e32 v25, 0, v25
	v_mul_f32_e32 v24, v24, v24
	v_pk_mul_f32 v[16:17], v[16:17], v[154:155] op_sel_hi:[1,0]
	v_pk_mul_f32 v[14:15], v[14:15], v[154:155] op_sel_hi:[1,0]
	v_mul_f32_e32 v26, v26, v26
	v_mul_f32_e32 v25, v25, v25
	v_cvt_pk_bf16_f32 v22, v26, v22
	v_cvt_pk_bf16_f32 v23, v23, v24
	v_cvt_pk_bf16_f32 v24, v194, v27
	s_mov_b64 s[22:23], 0x60000
	v_pk_mul_f32 v[20:21], v[20:21], v[154:155] op_sel_hi:[1,0]
	v_pk_mul_f32 v[18:19], v[18:19], v[154:155] op_sel_hi:[1,0]
	v_max_f32_e32 v14, 0, v14
	v_max_f32_e32 v15, 0, v15
	v_max_f32_e32 v16, 0, v16
	s_mov_b32 s13, 0x60000
	v_cvt_pk_bf16_f32 v25, v28, v25
	v_max_f32_e32 v17, 0, v17
	v_pk_mul_f32 v[6:7], v[6:7], v[154:155] op_sel_hi:[1,0]
	v_mul_f32_e32 v194, v14, v14
	v_max_f32_e32 v14, 0, v19
	v_mul_f32_e32 v19, v15, v15
	v_max_f32_e32 v15, 0, v20
	v_mul_f32_e32 v20, v16, v16
	v_max_f32_e32 v16, 0, v21
	v_max_f32_e32 v18, 0, v18
	v_mul_f32_e32 v14, v14, v14
	v_mul_f32_e32 v15, v15, v15
	v_mul_f32_e32 v16, v16, v16
	v_mul_f32_e32 v17, v17, v17
	v_pk_mul_f32 v[10:11], v[10:11], v[154:155] op_sel_hi:[1,0]
	v_pk_mul_f32 v[8:9], v[8:9], v[154:155] op_sel_hi:[1,0]
	v_max_f32_e32 v6, 0, v6
	v_max_f32_e32 v7, 0, v7
	v_mul_f32_e32 v18, v18, v18
	v_cvt_pk_bf16_f32 v14, v18, v14
	v_cvt_pk_bf16_f32 v15, v15, v16
	v_cvt_pk_bf16_f32 v16, v194, v19
	v_cvt_pk_bf16_f32 v17, v20, v17
	v_pk_mul_f32 v[2:3], v[12:13], v[154:155] op_sel_hi:[1,0]
	v_mul_f32_e32 v12, v6, v6
	v_max_f32_e32 v6, 0, v11
	v_mul_f32_e32 v11, v7, v7
	v_max_f32_e32 v7, 0, v8
	v_mul_f32_e32 v13, v7, v7
	v_max_f32_e32 v7, 0, v9
	v_max_f32_e32 v10, 0, v10
	v_mul_f32_e32 v6, v6, v6
	v_max_f32_e32 v2, 0, v2
	v_max_f32_e32 v3, 0, v3
	v_mul_f32_e32 v9, v7, v7
	v_mul_f32_e32 v10, v10, v10
	v_mul_f32_e32 v2, v2, v2
	v_mul_f32_e32 v3, v3, v3
	v_cvt_pk_bf16_f32 v6, v10, v6
	v_cvt_pk_bf16_f32 v7, v2, v3
	v_cvt_pk_bf16_f32 v8, v12, v11
	v_cvt_pk_bf16_f32 v9, v13, v9
	s_nop 1
	v_permlane32_swap_b32_e32 v30, v22
	v_permlane32_swap_b32_e32 v31, v23
	v_permlane32_swap_b32_e32 v32, v24
	v_permlane32_swap_b32_e32 v33, v25
	v_permlane32_swap_b32_e32 v14, v6
	v_permlane32_swap_b32_e32 v15, v7
	v_permlane32_swap_b32_e32 v16, v8
	v_permlane32_swap_b32_e32 v17, v9
	v_permlane16_swap_b32_e32 v30, v14
	v_permlane16_swap_b32_e32 v31, v15
	v_permlane16_swap_b32_e32 v32, v16
	v_permlane16_swap_b32_e32 v33, v17
	v_permlane16_swap_b32_e32 v22, v6
	v_permlane16_swap_b32_e32 v23, v7
	v_permlane16_swap_b32_e32 v24, v8
	v_permlane16_swap_b32_e32 v25, v9
	s_mov_b32 vcc_lo, 0x55555555
	s_mov_b32 vcc_hi, 0x55555555
	v_cndmask_b32_dpp v176, v14, v30, vcc quad_perm:[1,0,3,2] row_mask:0xf bank_mask:0xf
	v_cndmask_b32_dpp v177, v15, v31, vcc quad_perm:[1,0,3,2] row_mask:0xf bank_mask:0xf
	v_cndmask_b32_dpp v178, v16, v32, vcc quad_perm:[1,0,3,2] row_mask:0xf bank_mask:0xf
	v_cndmask_b32_dpp v179, v17, v33, vcc quad_perm:[1,0,3,2] row_mask:0xf bank_mask:0xf
	v_cndmask_b32_dpp v180, v6, v22, vcc quad_perm:[1,0,3,2] row_mask:0xf bank_mask:0xf
	v_cndmask_b32_dpp v181, v7, v23, vcc quad_perm:[1,0,3,2] row_mask:0xf bank_mask:0xf
	v_cndmask_b32_dpp v182, v8, v24, vcc quad_perm:[1,0,3,2] row_mask:0xf bank_mask:0xf
	v_cndmask_b32_dpp v183, v9, v25, vcc quad_perm:[1,0,3,2] row_mask:0xf bank_mask:0xf
	s_mov_b32 vcc_lo, 0xaaaaaaaa
	s_mov_b32 vcc_hi, 0xaaaaaaaa
	v_cndmask_b32_dpp v184, v30, v14, vcc quad_perm:[1,0,3,2] row_mask:0xf bank_mask:0xf
	v_cndmask_b32_dpp v185, v31, v15, vcc quad_perm:[1,0,3,2] row_mask:0xf bank_mask:0xf
	v_cndmask_b32_dpp v186, v32, v16, vcc quad_perm:[1,0,3,2] row_mask:0xf bank_mask:0xf
	v_cndmask_b32_dpp v187, v33, v17, vcc quad_perm:[1,0,3,2] row_mask:0xf bank_mask:0xf
	v_cndmask_b32_dpp v188, v22, v6, vcc quad_perm:[1,0,3,2] row_mask:0xf bank_mask:0xf
	v_cndmask_b32_dpp v189, v23, v7, vcc quad_perm:[1,0,3,2] row_mask:0xf bank_mask:0xf
	v_cndmask_b32_dpp v190, v24, v8, vcc quad_perm:[1,0,3,2] row_mask:0xf bank_mask:0xf
	v_cndmask_b32_dpp v191, v25, v9, vcc quad_perm:[1,0,3,2] row_mask:0xf bank_mask:0xf
	s_mov_b32 vcc_lo, 0x33333333
	s_mov_b32 vcc_hi, 0x33333333
	v_cndmask_b32_dpp v30, v180, v176, vcc quad_perm:[2,3,0,1] row_mask:0xf bank_mask:0xf
	v_cndmask_b32_dpp v31, v181, v177, vcc quad_perm:[2,3,0,1] row_mask:0xf bank_mask:0xf
	v_cndmask_b32_dpp v32, v182, v178, vcc quad_perm:[2,3,0,1] row_mask:0xf bank_mask:0xf
	v_cndmask_b32_dpp v33, v183, v179, vcc quad_perm:[2,3,0,1] row_mask:0xf bank_mask:0xf
	v_cndmask_b32_dpp v14, v188, v184, vcc quad_perm:[2,3,0,1] row_mask:0xf bank_mask:0xf
	v_cndmask_b32_dpp v15, v189, v185, vcc quad_perm:[2,3,0,1] row_mask:0xf bank_mask:0xf
	v_cndmask_b32_dpp v16, v190, v186, vcc quad_perm:[2,3,0,1] row_mask:0xf bank_mask:0xf
	v_cndmask_b32_dpp v17, v191, v187, vcc quad_perm:[2,3,0,1] row_mask:0xf bank_mask:0xf
	s_mov_b32 vcc_lo, 0xcccccccc
	s_mov_b32 vcc_hi, 0xcccccccc
	v_cndmask_b32_dpp v22, v176, v180, vcc quad_perm:[2,3,0,1] row_mask:0xf bank_mask:0xf
	v_cndmask_b32_dpp v23, v177, v181, vcc quad_perm:[2,3,0,1] row_mask:0xf bank_mask:0xf
	v_cndmask_b32_dpp v24, v178, v182, vcc quad_perm:[2,3,0,1] row_mask:0xf bank_mask:0xf
	v_cndmask_b32_dpp v25, v179, v183, vcc quad_perm:[2,3,0,1] row_mask:0xf bank_mask:0xf
	v_cndmask_b32_dpp v6, v184, v188, vcc quad_perm:[2,3,0,1] row_mask:0xf bank_mask:0xf
	v_cndmask_b32_dpp v7, v185, v189, vcc quad_perm:[2,3,0,1] row_mask:0xf bank_mask:0xf
	v_cndmask_b32_dpp v8, v186, v190, vcc quad_perm:[2,3,0,1] row_mask:0xf bank_mask:0xf
	v_cndmask_b32_dpp v9, v187, v191, vcc quad_perm:[2,3,0,1] row_mask:0xf bank_mask:0xf
	v_add_u32_e32 v192, 0x140000, v175
	global_store_dwordx4 v192, v[30:33], s[4:5] sc1
	v_add_u32_e32 v193, 0x142000, v175
	global_store_dwordx4 v193, v[14:17], s[4:5] sc1
	v_add_u32_e32 v195, 0x144000, v175
	global_store_dwordx4 v195, v[22:25], s[4:5] sc1
	v_add_u32_e32 v196, 0x146000, v175
	global_store_dwordx4 v196, v[6:9], s[4:5] sc1
	s_andn2_b64 vcc, exec, s[20:21]
	s_mov_b64 s[20:21], -1
	s_cbranch_vccnz .LBB0_936
	s_andn2_b64 vcc, exec, s[2:3]
	s_cbranch_vccnz .LBB0_935
	s_barrier
	s_branch .LBB0_935
